# same as previous (rewritten grid barrier with per-XCD replicated release counters, early L1 invalidate), spin cap raised to 2^20 polls
# speedup vs baseline: 1.0229x; 1.0045x over previous
; #define XB_SPIN(cond, bar) do { unsigned _sp = 0; while (cond) { __builtin_amdgcn_s_sleep(1); \
;     if ((++_sp & 255u) == 0u) { if (xb_ld(&(bar)[XB_TMO])) break; if (_sp > XB_SPIN_CAP) { atomicAdd(&(bar)[XB_TMO], 1u); break; } } } } while (0)
; __device__ __forceinline__ unsigned xb_ld(unsigned* p)              { return __hip_atomic_load(p, __ATOMIC_RELAXED, __HIP_MEMORY_SCOPE_AGENT); }
; __device__ __forceinline__ unsigned xb_add(unsigned* p, unsigned v) { return __hip_atomic_fetch_add(p, v, __ATOMIC_RELAXED, __HIP_MEMORY_SCOPE_AGENT); }
; __device__ __forceinline__ unsigned xb_xcc_id() { return (unsigned)__builtin_amdgcn_s_getreg((3 << 11) | 20) & 0xFu; }
; __device__ __forceinline__ void xcd_barrier(const XcdBarrier& b) {
;     asm volatile("s_waitcnt vmcnt(0)" ::: "memory");
;     __syncthreads();
;     if (threadIdx.x == 0) {
;         unsigned* bar = b.bar;
;         __builtin_amdgcn_s_waitcnt(0);
;         unsigned nloc = b.st[0], nx = b.st[1];
;         if (nloc == 0u) { xcd_barrier_complete(bar, b.x, nloc, nx); b.st[0] = nloc; b.st[1] = nx; }
;         const unsigned old = xb_add(&bar[XB_XSUB(b.x)], 1u);
;         const unsigned gen = old / nloc;
;         if (old + 1u == (gen + 1u) * nloc) {
;             __builtin_amdgcn_fence(__ATOMIC_RELEASE, "agent");
;             asm volatile("s_waitcnt vmcnt(0)" ::: "memory");
;             const unsigned og = xb_add(&bar[XB_TOP], 1u);
;             const unsigned tg = og / nx;
;             if (og + 1u == (tg + 1u) * nx) xb_add(&bar[XB_TOPGEN], 1u);
;             else XB_SPIN(xb_ld(&bar[XB_TOPGEN]) == tg, bar);
;             __builtin_amdgcn_fence(__ATOMIC_ACQUIRE, "agent");
;             xb_add(&bar[XB_XGEN(b.x)], 1u);
;             asm volatile("s_waitcnt vmcnt(0)" ::: "memory");
;         } else {
;             XB_SPIN(xb_ld(&bar[XB_XGEN(b.x)]) == gen, bar);
;             __builtin_amdgcn_fence(__ATOMIC_ACQUIRE, "agent");
;             asm volatile("s_waitcnt vmcnt(0)" ::: "memory");
;         }
;     }
;     __syncthreads();
; }
.Lnb_loop_1:
	s_sleep 1
	v_mov_b32_e32 v9, 0x2404
	global_load_dword v8, v9, s[12:13] sc1
	s_add_u32 s8, s8, 1
	s_cmp_gt_u32 s8, 0x100000
	s_cbranch_scc1 .Lnb_done_1
	s_waitcnt vmcnt(0)
	v_cmp_lt_u32_e32 vcc, v8, v7
	s_cbranch_vccnz .Lnb_loop_1
